# v31 + attention B/C/D per-tile DMA: slot address added straight into m0 (s_add_i32 m0) instead of add + s_mov, dead add-zero removed
# baseline (speedup 1.0000x reference)
; template <int DQK, int DV, bool BAND>
; DI void attn_unit(const AttnArgs& a, LAS unsigned char* lds, int tid) {
;     ...
;             vnext = vcur == 32768 ? 0 : vcur + 16384; const int vnn = vnext == 32768 ? 0 : vnext + 16384;
;             if (t + 2 < t_hi) AT_DMA(t + 2, vnn);
.LBB0_193:
	s_add_i32 s24, s48, 0x4000
	s_cmpk_lg_u32 s48, 0x8000
	s_cselect_b32 s24, s24, 0
	s_add_i32 s40, s24, 0
	s_add_i32 m0, s40, s83
	s_nop 0
	global_load_lds_dwordx4 v[66:67], off
	s_and_b64 vcc, exec, s[44:45]
	v_mov_b64_e32 v[66:67], v[178:179]
	s_cbranch_vccnz .LBB0_195
	v_lshl_add_u64 v[66:67], s[54:55], 0, v[64:65]

.Ld_skip_lp:
	s_add_i32 m0, s89, s24
	s_nop 0
	global_load_lds_dwordx4 v[174:175], off

; template <int DQK, int DV, bool BAND>
; DI void attn_unit(const AttnArgs& a, LAS unsigned char* lds, int tid) {
;     ...
;             vnext = vcur == 32768 ? 0 : vcur + 16384; const int vnn = vnext == 32768 ? 0 : vnext + 16384;
;             if (t + 2 < t_hi) AT_DMA(t + 2, vnn);
.LBB0_214:
	s_add_i32 s35, s48, 0x4000
	s_cmpk_lg_u32 s48, 0x8000
	s_cselect_b32 s35, s35, 0
	s_cmp_ge_u32 s34, s69
	s_cbranch_scc1 .LBB0_216
	s_add_i32 s46, s35, 0x4000
	s_cmpk_lg_u32 s35, 0x8000
	s_cselect_b32 s46, s46, 0
	s_add_i32 m0, s26, s46
	s_nop 0
	global_load_lds_dwordx4 v[200:201], off
	s_add_i32 s46, s46, 0xc000
	s_add_i32 m0, s46, s24
	s_nop 0
	global_load_lds_dwordx4 v[190:191], off
	s_add_i32 m0, s46, s27
	s_nop 0
	global_load_lds_dwordx4 v[198:199], off

; template <int DQK, int DV, bool BAND>
; DI void attn_unit(const AttnArgs& a, LAS unsigned char* lds, int tid) {
;     ...
;             vnext = vcur == 32768 ? 0 : vcur + 16384; const int vnn = vnext == 32768 ? 0 : vnext + 16384;
;             if (t + 2 < t_hi) AT_DMA(t + 2, vnn);
.LBB0_241:
	s_add_i32 s24, s26, 0x4000
	s_cmpk_lg_u32 s26, 0x8000
	s_cselect_b32 s24, s24, 0
	s_add_i32 s27, s27, 2
	s_cmp_ge_u32 s27, s69
	s_cbranch_scc1 .LBB0_243
	s_add_i32 s27, s24, 0x4000
	s_cmpk_lg_u32 s24, 0x8000
	s_cselect_b32 s27, s27, 0
	s_add_i32 m0, s17, s27
	s_nop 0
	global_load_lds_dwordx4 v[158:159], off
	s_add_i32 m0, s18, s27
	s_nop 0
	global_load_lds_dwordx4 v[156:157], off
